# instruction-side warm-up with 64 KiB per seam (was 32 KiB), stacked on v85
# speedup vs baseline: 1.0029x; 1.0029x over previous
.Lcpf_pc_0:
	s_add_u32 s98, s98, .LBB0_189-.Lcpf_pc_0
	s_addc_u32 s99, s99, 0
	v_lshlrev_b32_e32 v252, 7, v186
	global_load_dword v253, v252, s[98:99]
	s_add_u32 s98, s98, 0x2000
	s_addc_u32 s99, s99, 0
	global_load_dword v253, v252, s[98:99]
	s_add_u32 s98, s98, 0x2000
	s_addc_u32 s99, s99, 0
	global_load_dword v253, v252, s[98:99]
	s_add_u32 s98, s98, 0x2000
	s_addc_u32 s99, s99, 0
	global_load_dword v253, v252, s[98:99]
	s_add_u32 s98, s98, 0x2000
	s_addc_u32 s99, s99, 0
	global_load_dword v253, v252, s[98:99]
	s_add_u32 s98, s98, 0x2000
	s_addc_u32 s99, s99, 0
	global_load_dword v253, v252, s[98:99]
	s_add_u32 s98, s98, 0x2000
	s_addc_u32 s99, s99, 0
	global_load_dword v253, v252, s[98:99]
	s_add_u32 s98, s98, 0x2000
	s_addc_u32 s99, s99, 0
	global_load_dword v253, v252, s[98:99]
